# MoBA gate loop: next q-chunk load issued one iteration ahead (was load -> vmcnt(0) -> use per iteration)
# speedup vs baseline: 1.0078x; 1.0042x over previous
; #define LAS __attribute__((address_space(3)))
; __device__ __forceinline__ void moba_select(LAS unsigned char* lds, const bf16_t* Qp, int ld, int rowbase, int ob, const float* kmean_bh) {
;     ...
;     __syncthreads();
;     ((LAS f32x4*)km_s)[tid] = ((const f32x4*)kmean_bh)[tid];
;     __syncthreads();
;     { const int q = tid >> 1, par = tid & 1; const bf16_t* qrow = Qp + (size_t)(rowbase + ob * 256 + q) * ld;
;       float acc[8];
; #pragma unroll
;       for (int jj = 0; jj < 8; ++jj) acc[jj] = 0.f;
;       for (int c = 0; c < 16; ++c) {
;           const u32x4 qv = *(const u32x4*)(qrow + c * 8);
;           float qfv[8]; qfv[0] = bflo(qv.x); qfv[1] = bfhi(qv.x); qfv[2] = bflo(qv.y); qfv[3] = bfhi(qv.y); qfv[4] = bflo(qv.z); qfv[5] = bfhi(qv.z); qfv[6] = bflo(qv.w); qfv[7] = bfhi(qv.w);
; #pragma unroll
;           for (int jj = 0; jj < 8; ++jj) { const int j = 2 * jj + par;
;               if (j < ob) { const LAS float* km = km_s + j * 128 + c * 8; const f32x4 ka = *(const LAS f32x4*)km, kb = *(const LAS f32x4*)(km + 4);
;                   acc[jj] += qfv[0] * ka[0] + qfv[1] * ka[1] + qfv[2] * ka[2] + qfv[3] * ka[3] + qfv[4] * kb[0] + qfv[5] * kb[1] + qfv[6] * kb[2] + qfv[7] * kb[3]; } }
;       }
.LBB0_889:
	s_barrier
	global_load_dwordx4 v[24:27], v[154:155], off
	s_xor_b64 s[52:53], s[54:55], -1
	s_and_b64 s[2:3], s[54:55], exec
	s_cselect_b32 s35, s65, s64
	s_lshl_b32 s36, s35, 8
	s_waitcnt vmcnt(22)
	v_mov_b64_e32 v[28:29], s[50:51]
	v_mov_b32_e32 v6, v1
	v_mov_b32_e32 v7, v1
	v_add_u32_e32 v30, s36, v149
	v_mov_b32_e32 v0, v1
	v_mov_b32_e32 v2, v1
	v_mov_b32_e32 v3, v1
	v_mov_b32_e32 v4, v1
	v_mov_b32_e32 v5, v1
	v_mad_i64_i32 v[32:33], s[16:17], v30, s94, v[28:29]
	s_mov_b32 s18, 0
	v_cmp_gt_u32_e32 vcc, s35, v172
	v_cmp_gt_u32_e64 s[2:3], s35, v173
	v_cmp_gt_u32_e64 s[4:5], s35, v174
	v_cmp_gt_u32_e64 s[6:7], s35, v175
	v_cmp_gt_u32_e64 s[8:9], s35, v176
	v_cmp_gt_u32_e64 s[10:11], s35, v177
	v_cmp_gt_u32_e64 s[12:13], s35, v178
	v_cmp_gt_u32_e64 s[14:15], s35, v179
	s_waitcnt vmcnt(0)
	ds_write_b128 v170, v[24:27]
	v_mov_b64_e32 v[30:31], v[6:7]
	v_mov_b64_e32 v[28:29], v[4:5]
	v_mov_b64_e32 v[26:27], v[2:3]
	v_mov_b64_e32 v[24:25], v[0:1]
	global_load_dwordx4 v[230:233], v[32:33], off
	s_waitcnt lgkmcnt(0)
	s_barrier
	s_branch .LBB0_891
.LBB0_890:
	s_or_b64 exec, exec, s[16:17]
	s_add_i32 s18, s18, 32
	s_cmpk_eq_i32 s18, 0x200
	s_cbranch_scc1 .LBB0_907
.LBB0_891:
	v_add_u32_e32 v0, s18, v182
	s_waitcnt vmcnt(0)
	v_lshlrev_b32_e32 v2, 16, v230
	v_and_b32_e32 v3, 0xffff0000, v230
	v_and_b32_e32 v5, 0xffff0000, v231
	v_lshlrev_b32_e32 v4, 16, v231
	v_and_b32_e32 v7, 0xffff0000, v232
	v_lshlrev_b32_e32 v6, 16, v232
	v_and_b32_e32 v35, 0xffff0000, v233
	v_lshlrev_b32_e32 v34, 16, v233
	v_lshl_add_u64 v[32:33], v[32:33], 0, 16
	global_load_dwordx4 v[230:233], v[32:33], off
	s_and_saveexec_b64 s[16:17], vcc
	s_cbranch_execnz .LBB0_899
	s_or_b64 exec, exec, s[16:17]
	s_and_saveexec_b64 s[16:17], s[2:3]
	s_cbranch_execnz .LBB0_900
